# bundle: phase-0 pre-norm gain vector loaded once, hyena filter copies unrolled, attnC step maximum only on the re-basing path
# speedup vs baseline: 1.0399x; 1.0121x over previous
; #define LAS __attribute__((address_space(3)))
; __device__ __forceinline__ unsigned pk2n(float lo, float hi) { const f32x2v v = {lo, hi}; const bf16v2 b = __builtin_convertvector(v, bf16v2); return __builtin_bit_cast(unsigned, b); }
; __device__ __forceinline__ float fexp2(float x) { return __builtin_amdgcn_exp2f(x); }
; template <bool KLDS>
; __device__ __forceinline__ void attn_step(const bf16x8 (&kf)[4], LAS const unsigned char* kb, const bf16x8 (&vf)[2][2], const bf16x8 (&qf)[4], f32x16& o0, f32x16& o1, float& m, float& l, int lane, int maskmode) {
;     ...
;     float tm = S[0];
; #pragma unroll
;     for (int i = 1; i < 16; ++i) tm = fmaxf(tm, S[i]);
;     tm = fmaxf(tm, __shfl_xor(tm, 32));
;     const float mn = fmaxf(m, tm), al = fexp2(m - mn); m = mn;
;     float ps = 0.f;
; #pragma unroll
;     for (int i = 0; i < 16; ++i) { S[i] = fexp2(S[i] - mn); ps += S[i]; }
;     l = l * al + ps;
; #pragma unroll
;     for (int i = 0; i < 16; ++i) { o0[i] *= al; o1[i] *= al; }
;     bf16x8 pf[2];
; #pragma unroll
;     for (int s2 = 0; s2 < 2; ++s2) {
;         u32x4 w; w.x = pk2n(S[8 * s2 + 0], S[8 * s2 + 1]); w.y = pk2n(S[8 * s2 + 2], S[8 * s2 + 3]); w.z = pk2n(S[8 * s2 + 4], S[8 * s2 + 5]); w.w = pk2n(S[8 * s2 + 6], S[8 * s2 + 7]);
;         pf[s2] = __builtin_bit_cast(bf16x8, w);
;     }
; #pragma unroll
;     for (int s2 = 0; s2 < 2; ++s2) {
;         o0 = __builtin_amdgcn_mfma_f32_32x32x16_bf16(vf[s2][0], pf[s2], o0, 0, 0, 0);
;         o1 = __builtin_amdgcn_mfma_f32_32x32x16_bf16(vf[s2][1], pf[s2], o1, 0, 0, 0);
;     }
; __device__ __forceinline__ void attnC_unit(const Args& a, int unit, LAS unsigned char* lds) {
;     ...
;     for (int kt = 0; kt < 32; ++kt) {
;         LAS unsigned char* cur = lds + (kt & 1) * 16384;
;         LAS unsigned char* nxt = lds + ((kt + 1) & 1) * 16384;
;         if (kt + 1 < 32) { *(LAS u32x4*)(nxt + kwo) = rk; *(LAS u32x4*)(nxt + vwo) = rv; }
;         if (kt + 2 < 32) { rk = *(const u32x4*)(kg + (size_t)(kt + 2) * TSTEP); rv = *(const u32x4*)(vg + (size_t)(kt + 2) * TSTEP); }
; #pragma unroll
;         for (int j = 0; j < 2; ++j) {
;             bf16x8 kf[4], vf[2][2];
;             load_kf(cur + j * 4096, kf, lane); load_vf(cur + 8192 + j * 4096, vf, lane);
; #pragma unroll
;             for (int e = 0; e < 2; ++e) attn_step<false>(kf, cur, vf, qf[e], o0[e], o1[e], m[e], l[e], lane, 0);
;         }
;         __syncthreads();
.LaN_nd:
	s_mov_b32 s34, 0x71800000
	v_add3_u32 v137, s29, v157, v156
	v_add3_u32 v142, s29, v252, v231
	v_add3_u32 v143, s29, v252, v239
	v_add3_u32 v144, s29, v252, v232
	v_add3_u32 v145, s29, v252, v241
	ds_read_b128 v[112:115], v142
	ds_read_b128 v[116:119], v143
	ds_read_b128 v[216:219], v144
	ds_read_b128 v[220:223], v145
	ds_read_b64_tr_b16 v[146:147], v137 offset:8192
	ds_read_b64_tr_b16 v[148:149], v137 offset:9216
	ds_read_b64_tr_b16 v[204:205], v137 offset:8256
	ds_read_b64_tr_b16 v[206:207], v137 offset:9280
	ds_read_b64_tr_b16 v[208:209], v137 offset:10240
	ds_read_b64_tr_b16 v[210:211], v137 offset:11264
	ds_read_b64_tr_b16 v[212:213], v137 offset:10304
	ds_read_b64_tr_b16 v[214:215], v137 offset:11328
	s_waitcnt lgkmcnt(11)
	v_mfma_f32_32x32x16_bf16 v[64:79], v[112:115], v[80:83], v[182:197]
	v_mfma_f32_32x32x16_bf16 v[158:173], v[112:115], v[96:99], v[120:135]
	s_waitcnt lgkmcnt(10)
	v_mfma_f32_32x32x16_bf16 v[64:79], v[116:119], v[84:87], v[64:79]
	v_mfma_f32_32x32x16_bf16 v[158:173], v[116:119], v[100:103], v[158:173]
	s_waitcnt lgkmcnt(9)
	v_mfma_f32_32x32x16_bf16 v[64:79], v[216:219], v[88:91], v[64:79]
	v_mfma_f32_32x32x16_bf16 v[158:173], v[216:219], v[104:107], v[158:173]
	s_waitcnt lgkmcnt(8)
	v_mfma_f32_32x32x16_bf16 v[64:79], v[220:223], v[92:95], v[64:79]
	v_mfma_f32_32x32x16_bf16 v[158:173], v[220:223], v[108:111], v[158:173]
	s_nop 10
	s_cmp_eq_u32 s3, 0
	s_cbranch_scc1 .LaN_fs
.LaN_xj0:
	v_exp_f32_e32 v64, v64
	v_exp_f32_e32 v158, v158
	v_exp_f32_e32 v65, v65
	v_exp_f32_e32 v159, v159
	v_exp_f32_e32 v66, v66
	v_exp_f32_e32 v160, v160
	v_add_f32_e32 v138, v64, v65
	v_add_f32_e32 v140, v158, v159
	v_exp_f32_e32 v67, v67
	v_exp_f32_e32 v161, v161
	v_add_f32_e32 v139, v66, v67
	v_add_f32_e32 v141, v160, v161
	v_exp_f32_e32 v68, v68
	v_exp_f32_e32 v162, v162
	v_exp_f32_e32 v69, v69
	v_exp_f32_e32 v163, v163
	v_add_f32_e32 v139, v139, v68
	v_add_f32_e32 v141, v141, v162
	v_exp_f32_e32 v70, v70
	v_exp_f32_e32 v164, v164
	v_add_f32_e32 v138, v138, v69
	v_add_f32_e32 v140, v140, v163
	v_exp_f32_e32 v71, v71
	v_exp_f32_e32 v165, v165
	v_add_f32_e32 v139, v139, v70
	v_add_f32_e32 v141, v141, v164
	v_exp_f32_e32 v72, v72
	v_exp_f32_e32 v166, v166
	v_add_f32_e32 v138, v138, v71
	v_add_f32_e32 v140, v140, v165
	v_exp_f32_e32 v73, v73
	v_exp_f32_e32 v167, v167
	v_add_f32_e32 v139, v139, v72
	v_add_f32_e32 v141, v141, v166
	v_exp_f32_e32 v74, v74
	v_exp_f32_e32 v168, v168
	v_add_f32_e32 v138, v138, v73
	v_add_f32_e32 v140, v140, v167
	v_exp_f32_e32 v75, v75
	v_exp_f32_e32 v169, v169
	v_add_f32_e32 v139, v139, v74
	v_add_f32_e32 v141, v141, v168
	v_exp_f32_e32 v76, v76
	v_exp_f32_e32 v170, v170
	v_add_f32_e32 v138, v138, v75
	v_add_f32_e32 v140, v140, v169
	v_exp_f32_e32 v77, v77
	v_exp_f32_e32 v171, v171
	v_add_f32_e32 v139, v139, v76
	v_add_f32_e32 v141, v141, v170
	v_exp_f32_e32 v78, v78
	v_exp_f32_e32 v172, v172
	v_add_f32_e32 v138, v138, v77
	v_add_f32_e32 v140, v140, v171
	v_exp_f32_e32 v79, v79
	v_exp_f32_e32 v173, v173
	v_add_f32_e32 v139, v139, v78
	v_add_f32_e32 v141, v141, v172
	s_nop 0
	s_nop 0
	v_add_f32_e32 v139, v139, v79
	v_add_f32_e32 v141, v141, v173
	v_add_f32_e32 v138, v138, v139
	v_add_f32_e32 v140, v140, v141
	v_cmp_lt_f32_e64 s[10:11], s34, v138
	v_cmp_lt_f32_e64 s[4:5], s34, v140
	s_nop 0
	s_or_b64 vcc, s[10:11], s[4:5]
	s_cbranch_vccnz .LaN_ovj0
	v_add_f32_e32 v179, v179, v138
	v_add_f32_e32 v178, v178, v140
	v_cvt_pk_bf16_f32 v64, v64, v65
	v_cvt_pk_bf16_f32 v158, v158, v159
	v_cvt_pk_bf16_f32 v65, v66, v67
	v_cvt_pk_bf16_f32 v159, v160, v161
	v_cvt_pk_bf16_f32 v66, v68, v69
	v_cvt_pk_bf16_f32 v160, v162, v163
	v_cvt_pk_bf16_f32 v67, v70, v71
	v_cvt_pk_bf16_f32 v161, v164, v165
	v_cvt_pk_bf16_f32 v68, v72, v73
	v_cvt_pk_bf16_f32 v162, v166, v167
	v_cvt_pk_bf16_f32 v69, v74, v75
	v_cvt_pk_bf16_f32 v163, v168, v169
	v_cvt_pk_bf16_f32 v70, v76, v77
	v_cvt_pk_bf16_f32 v164, v170, v171
	v_cvt_pk_bf16_f32 v71, v78, v79
	v_cvt_pk_bf16_f32 v165, v172, v173
	s_waitcnt lgkmcnt(0)
	v_mfma_f32_32x32x16_bf16 v[48:63], v[146:149], v[64:67], v[48:63]
	v_mfma_f32_32x32x16_bf16 v[16:31], v[146:149], v[158:161], v[16:31]
	v_mfma_f32_32x32x16_bf16 v[32:47], v[204:207], v[64:67], v[32:47]
	v_mfma_f32_32x32x16_bf16 v[0:15], v[204:207], v[158:161], v[0:15]
	v_mfma_f32_32x32x16_bf16 v[48:63], v[208:211], v[68:71], v[48:63]
	v_mfma_f32_32x32x16_bf16 v[16:31], v[208:211], v[162:165], v[16:31]
	v_mfma_f32_32x32x16_bf16 v[32:47], v[212:215], v[68:71], v[32:47]
	v_mfma_f32_32x32x16_bf16 v[0:15], v[212:215], v[162:165], v[0:15]
	ds_read_b128 v[112:115], v142 offset:4096
	ds_read_b128 v[116:119], v143 offset:4096
	ds_read_b128 v[216:219], v144 offset:4096
	ds_read_b128 v[220:223], v145 offset:4096
	ds_read_b64_tr_b16 v[146:147], v137 offset:12288
	ds_read_b64_tr_b16 v[148:149], v137 offset:13312
	ds_read_b64_tr_b16 v[204:205], v137 offset:12352
	ds_read_b64_tr_b16 v[206:207], v137 offset:13376
	ds_read_b64_tr_b16 v[208:209], v137 offset:14336
	ds_read_b64_tr_b16 v[210:211], v137 offset:15360
	ds_read_b64_tr_b16 v[212:213], v137 offset:14400
	ds_read_b64_tr_b16 v[214:215], v137 offset:15424
	s_waitcnt lgkmcnt(11)
	v_mfma_f32_32x32x16_bf16 v[64:79], v[112:115], v[80:83], v[182:197]
	v_mfma_f32_32x32x16_bf16 v[158:173], v[112:115], v[96:99], v[120:135]
	s_waitcnt lgkmcnt(10)
	v_mfma_f32_32x32x16_bf16 v[64:79], v[116:119], v[84:87], v[64:79]
	v_mfma_f32_32x32x16_bf16 v[158:173], v[116:119], v[100:103], v[158:173]
	s_waitcnt lgkmcnt(9)
	v_mfma_f32_32x32x16_bf16 v[64:79], v[216:219], v[88:91], v[64:79]
	v_mfma_f32_32x32x16_bf16 v[158:173], v[216:219], v[104:107], v[158:173]
	s_waitcnt lgkmcnt(8)
	v_mfma_f32_32x32x16_bf16 v[64:79], v[220:223], v[92:95], v[64:79]
	v_mfma_f32_32x32x16_bf16 v[158:173], v[220:223], v[108:111], v[158:173]
	s_nop 10
; #define LAS __attribute__((address_space(3)))
; __device__ __forceinline__ unsigned pk2n(float lo, float hi) { const f32x2v v = {lo, hi}; const bf16v2 b = __builtin_convertvector(v, bf16v2); return __builtin_bit_cast(unsigned, b); }
; __device__ __forceinline__ float fexp2(float x) { return __builtin_amdgcn_exp2f(x); }
; template <bool KLDS>
; __device__ __forceinline__ void attn_step(const bf16x8 (&kf)[4], LAS const unsigned char* kb, const bf16x8 (&vf)[2][2], const bf16x8 (&qf)[4], f32x16& o0, f32x16& o1, float& m, float& l, int lane, int maskmode) {
;     ...
;     float tm = S[0];
; #pragma unroll
;     for (int i = 1; i < 16; ++i) tm = fmaxf(tm, S[i]);
;     tm = fmaxf(tm, __shfl_xor(tm, 32));
;     const float mn = fmaxf(m, tm), al = fexp2(m - mn); m = mn;
;     float ps = 0.f;
; #pragma unroll
;     for (int i = 0; i < 16; ++i) { S[i] = fexp2(S[i] - mn); ps += S[i]; }
;     l = l * al + ps;
; #pragma unroll
;     for (int i = 0; i < 16; ++i) { o0[i] *= al; o1[i] *= al; }
;     bf16x8 pf[2];
; #pragma unroll
;     for (int s2 = 0; s2 < 2; ++s2) {
;         u32x4 w; w.x = pk2n(S[8 * s2 + 0], S[8 * s2 + 1]); w.y = pk2n(S[8 * s2 + 2], S[8 * s2 + 3]); w.z = pk2n(S[8 * s2 + 4], S[8 * s2 + 5]); w.w = pk2n(S[8 * s2 + 6], S[8 * s2 + 7]);
;         pf[s2] = __builtin_bit_cast(bf16x8, w);
;     }
; #pragma unroll
;     for (int s2 = 0; s2 < 2; ++s2) {
;         o0 = __builtin_amdgcn_mfma_f32_32x32x16_bf16(vf[s2][0], pf[s2], o0, 0, 0, 0);
;         o1 = __builtin_amdgcn_mfma_f32_32x32x16_bf16(vf[s2][1], pf[s2], o1, 0, 0, 0);
;     }
; __device__ __forceinline__ void attnC_unit(const Args& a, int unit, LAS unsigned char* lds) {
;     ...
;     for (int kt = 0; kt < 32; ++kt) {
;         LAS unsigned char* cur = lds + (kt & 1) * 16384;
;         LAS unsigned char* nxt = lds + ((kt + 1) & 1) * 16384;
;         if (kt + 1 < 32) { *(LAS u32x4*)(nxt + kwo) = rk; *(LAS u32x4*)(nxt + vwo) = rv; }
;         if (kt + 2 < 32) { rk = *(const u32x4*)(kg + (size_t)(kt + 2) * TSTEP); rv = *(const u32x4*)(vg + (size_t)(kt + 2) * TSTEP); }
; #pragma unroll
;         for (int j = 0; j < 2; ++j) {
;             bf16x8 kf[4], vf[2][2];
;             load_kf(cur + j * 4096, kf, lane); load_vf(cur + 8192 + j * 4096, vf, lane);
; #pragma unroll
;             for (int e = 0; e < 2; ++e) attn_step<false>(kf, cur, vf, qf[e], o0[e], o1[e], m[e], l[e], lane, 0);
;         }
;         __syncthreads();
.LaN_xj1:
	v_exp_f32_e32 v64, v64
	v_exp_f32_e32 v158, v158
	v_exp_f32_e32 v65, v65
	v_exp_f32_e32 v159, v159
	v_exp_f32_e32 v66, v66
	v_exp_f32_e32 v160, v160
	v_add_f32_e32 v138, v64, v65
	v_add_f32_e32 v140, v158, v159
	v_exp_f32_e32 v67, v67
	v_exp_f32_e32 v161, v161
	v_add_f32_e32 v139, v66, v67
	v_add_f32_e32 v141, v160, v161
	v_exp_f32_e32 v68, v68
	v_exp_f32_e32 v162, v162
	v_exp_f32_e32 v69, v69
	v_exp_f32_e32 v163, v163
	v_add_f32_e32 v139, v139, v68
	v_add_f32_e32 v141, v141, v162
	v_exp_f32_e32 v70, v70
	v_exp_f32_e32 v164, v164
	v_add_f32_e32 v138, v138, v69
	v_add_f32_e32 v140, v140, v163
	v_exp_f32_e32 v71, v71
	v_exp_f32_e32 v165, v165
	v_add_f32_e32 v139, v139, v70
	v_add_f32_e32 v141, v141, v164
	v_exp_f32_e32 v72, v72
	v_exp_f32_e32 v166, v166
	v_add_f32_e32 v138, v138, v71
	v_add_f32_e32 v140, v140, v165
	v_exp_f32_e32 v73, v73
	v_exp_f32_e32 v167, v167
	v_add_f32_e32 v139, v139, v72
	v_add_f32_e32 v141, v141, v166
	v_exp_f32_e32 v74, v74
	v_exp_f32_e32 v168, v168
	v_add_f32_e32 v138, v138, v73
	v_add_f32_e32 v140, v140, v167
	v_exp_f32_e32 v75, v75
	v_exp_f32_e32 v169, v169
	v_add_f32_e32 v139, v139, v74
	v_add_f32_e32 v141, v141, v168
	v_exp_f32_e32 v76, v76
	v_exp_f32_e32 v170, v170
	v_add_f32_e32 v138, v138, v75
	v_add_f32_e32 v140, v140, v169
	v_exp_f32_e32 v77, v77
	v_exp_f32_e32 v171, v171
	v_add_f32_e32 v139, v139, v76
	v_add_f32_e32 v141, v141, v170
	v_exp_f32_e32 v78, v78
	v_exp_f32_e32 v172, v172
	v_add_f32_e32 v138, v138, v77
	v_add_f32_e32 v140, v140, v171
	v_exp_f32_e32 v79, v79
	v_exp_f32_e32 v173, v173
	v_add_f32_e32 v139, v139, v78
	v_add_f32_e32 v141, v141, v172
	s_nop 0
	s_nop 0
	v_add_f32_e32 v139, v139, v79
	v_add_f32_e32 v141, v141, v173
	v_add_f32_e32 v138, v138, v139
	v_add_f32_e32 v140, v140, v141
	v_cmp_lt_f32_e64 s[10:11], s34, v138
	v_cmp_lt_f32_e64 s[4:5], s34, v140
	s_nop 0
	s_or_b64 vcc, s[10:11], s[4:5]
	s_cbranch_vccnz .LaN_ovj1
	v_add_f32_e32 v179, v179, v138
	v_add_f32_e32 v178, v178, v140
	v_cvt_pk_bf16_f32 v64, v64, v65
	v_cvt_pk_bf16_f32 v158, v158, v159
	v_cvt_pk_bf16_f32 v65, v66, v67
	v_cvt_pk_bf16_f32 v159, v160, v161
	v_cvt_pk_bf16_f32 v66, v68, v69
	v_cvt_pk_bf16_f32 v160, v162, v163
	v_cvt_pk_bf16_f32 v67, v70, v71
	v_cvt_pk_bf16_f32 v161, v164, v165
	v_cvt_pk_bf16_f32 v68, v72, v73
	v_cvt_pk_bf16_f32 v162, v166, v167
	v_cvt_pk_bf16_f32 v69, v74, v75
	v_cvt_pk_bf16_f32 v163, v168, v169
	v_cvt_pk_bf16_f32 v70, v76, v77
	v_cvt_pk_bf16_f32 v164, v170, v171
	v_cvt_pk_bf16_f32 v71, v78, v79
	v_cvt_pk_bf16_f32 v165, v172, v173
	s_waitcnt lgkmcnt(0)
	v_mfma_f32_32x32x16_bf16 v[48:63], v[146:149], v[64:67], v[48:63]
	v_mfma_f32_32x32x16_bf16 v[16:31], v[146:149], v[158:161], v[16:31]
	v_mfma_f32_32x32x16_bf16 v[32:47], v[204:207], v[64:67], v[32:47]
	v_mfma_f32_32x32x16_bf16 v[0:15], v[204:207], v[158:161], v[0:15]
	v_mfma_f32_32x32x16_bf16 v[48:63], v[208:211], v[68:71], v[48:63]
	v_mfma_f32_32x32x16_bf16 v[16:31], v[208:211], v[162:165], v[16:31]
	v_mfma_f32_32x32x16_bf16 v[32:47], v[212:215], v[68:71], v[32:47]
	v_mfma_f32_32x32x16_bf16 v[0:15], v[212:215], v[162:165], v[0:15]
	s_mov_b32 s33, s29
	s_mov_b32 s29, s30
	s_mov_b32 s30, s31
	s_mov_b32 s31, s33
	s_add_i32 s3, s3, 1
	s_cmp_lg_u32 s3, 32
	s_cbranch_scc1 .LaN_loop
	s_nop 15
	s_nop 7
	s_branch .LBB0_252
.LaN_fs:
	s_mov_b32 s9, 0xff800000
	s_branch .LaN_slj0
.LaN_ovj0:
	v_mfma_f32_32x32x16_bf16 v[64:79], v[112:115], v[80:83], v[182:197]
	v_mfma_f32_32x32x16_bf16 v[158:173], v[112:115], v[96:99], v[120:135]
	v_mfma_f32_32x32x16_bf16 v[64:79], v[116:119], v[84:87], v[64:79]
	v_mfma_f32_32x32x16_bf16 v[158:173], v[116:119], v[100:103], v[158:173]
	v_mfma_f32_32x32x16_bf16 v[64:79], v[216:219], v[88:91], v[64:79]
	v_mfma_f32_32x32x16_bf16 v[158:173], v[216:219], v[104:107], v[158:173]
	v_mfma_f32_32x32x16_bf16 v[64:79], v[220:223], v[92:95], v[64:79]
	v_mfma_f32_32x32x16_bf16 v[158:173], v[220:223], v[108:111], v[158:173]
	s_mov_b32 s9, 0x41000000
; __device__ __forceinline__ float fexp2(float x) { return __builtin_amdgcn_exp2f(x); }
; template <bool KLDS>
; __device__ __forceinline__ void attn_step(const bf16x8 (&kf)[4], LAS const unsigned char* kb, const bf16x8 (&vf)[2][2], const bf16x8 (&qf)[4], f32x16& o0, f32x16& o1, float& m, float& l, int lane, int maskmode) {
;     ...
;     float tm = S[0];
; #pragma unroll
;     for (int i = 1; i < 16; ++i) tm = fmaxf(tm, S[i]);
;     tm = fmaxf(tm, __shfl_xor(tm, 32));
;     const float mn = fmaxf(m, tm), al = fexp2(m - mn); m = mn;
;     float ps = 0.f;
; #pragma unroll
;     for (int i = 0; i < 16; ++i) { S[i] = fexp2(S[i] - mn); ps += S[i]; }
;     l = l * al + ps;
; #pragma unroll
;     for (int i = 0; i < 16; ++i) { o0[i] *= al; o1[i] *= al; }
.LaN_slj0:
	s_nop 15
	s_nop 15
	v_max3_f32 v152, v64, v65, v66
	v_max3_f32 v152, v152, v67, v68
	v_max3_f32 v152, v152, v69, v70
	v_max3_f32 v152, v152, v71, v72
	v_max3_f32 v152, v152, v73, v74
	v_max3_f32 v152, v152, v75, v76
	v_max3_f32 v152, v152, v77, v78
	v_max_f32_e32 v152, v152, v79
	v_mov_b32_e32 v153, v152
	s_nop 1
	v_permlane32_swap_b32_e32 v153, v152
	v_max_f32_e32 v152, v152, v153
	v_cmp_lt_f32_e64 s[10:11], s9, v152
	s_nop 1
	v_cndmask_b32_e64 v154, 0, v152, s[10:11]
	v_sub_f32_e32 v64, v64, v154
	v_sub_f32_e32 v65, v65, v154
	v_sub_f32_e32 v66, v66, v154
	v_sub_f32_e32 v67, v67, v154
	v_sub_f32_e32 v68, v68, v154
	v_sub_f32_e32 v69, v69, v154
	v_sub_f32_e32 v70, v70, v154
	v_sub_f32_e32 v71, v71, v154
	v_sub_f32_e32 v72, v72, v154
	v_sub_f32_e32 v73, v73, v154
	v_sub_f32_e32 v74, v74, v154
	v_sub_f32_e32 v75, v75, v154
	v_sub_f32_e32 v76, v76, v154
	v_sub_f32_e32 v77, v77, v154
	v_sub_f32_e32 v78, v78, v154
	v_sub_f32_e32 v79, v79, v154
	v_sub_f32_e32 v182, v182, v154
	v_sub_f32_e32 v183, v183, v154
	v_sub_f32_e32 v184, v184, v154
	v_sub_f32_e32 v185, v185, v154
	v_sub_f32_e32 v186, v186, v154
	v_sub_f32_e32 v187, v187, v154
	v_sub_f32_e32 v188, v188, v154
	v_sub_f32_e32 v189, v189, v154
	v_sub_f32_e32 v190, v190, v154
	v_sub_f32_e32 v191, v191, v154
	v_sub_f32_e32 v192, v192, v154
	v_sub_f32_e32 v193, v193, v154
	v_sub_f32_e32 v194, v194, v154
	v_sub_f32_e32 v195, v195, v154
	v_sub_f32_e32 v196, v196, v154
	v_sub_f32_e32 v197, v197, v154
	s_cmp_eq_u32 s9, 0xff800000
	s_cbranch_scc1 .LaN_nrj00
	v_sub_f32_e32 v153, 0, v154
	v_exp_f32_e32 v154, v153
	s_nop 0
	v_mul_f32_e32 v179, v179, v154
	v_pk_mul_f32 v[48:49], v[48:49], v[154:155] op_sel_hi:[1,0]
	v_pk_mul_f32 v[50:51], v[50:51], v[154:155] op_sel_hi:[1,0]
	v_pk_mul_f32 v[52:53], v[52:53], v[154:155] op_sel_hi:[1,0]
	v_pk_mul_f32 v[54:55], v[54:55], v[154:155] op_sel_hi:[1,0]
	v_pk_mul_f32 v[56:57], v[56:57], v[154:155] op_sel_hi:[1,0]
	v_pk_mul_f32 v[58:59], v[58:59], v[154:155] op_sel_hi:[1,0]
	v_pk_mul_f32 v[60:61], v[60:61], v[154:155] op_sel_hi:[1,0]
	v_pk_mul_f32 v[62:63], v[62:63], v[154:155] op_sel_hi:[1,0]
	v_pk_mul_f32 v[32:33], v[32:33], v[154:155] op_sel_hi:[1,0]
	v_pk_mul_f32 v[34:35], v[34:35], v[154:155] op_sel_hi:[1,0]
	v_pk_mul_f32 v[36:37], v[36:37], v[154:155] op_sel_hi:[1,0]
	v_pk_mul_f32 v[38:39], v[38:39], v[154:155] op_sel_hi:[1,0]
	v_pk_mul_f32 v[40:41], v[40:41], v[154:155] op_sel_hi:[1,0]
	v_pk_mul_f32 v[42:43], v[42:43], v[154:155] op_sel_hi:[1,0]
	v_pk_mul_f32 v[44:45], v[44:45], v[154:155] op_sel_hi:[1,0]
	v_pk_mul_f32 v[46:47], v[46:47], v[154:155] op_sel_hi:[1,0]
.LaN_nrj00:
	v_max3_f32 v150, v158, v159, v160
	v_max3_f32 v150, v150, v161, v162
	v_max3_f32 v150, v150, v163, v164
	v_max3_f32 v150, v150, v165, v166
	v_max3_f32 v150, v150, v167, v168
	v_max3_f32 v150, v150, v169, v170
	v_max3_f32 v150, v150, v171, v172
	v_max_f32_e32 v150, v150, v173
	v_mov_b32_e32 v151, v150
	s_nop 1
	v_permlane32_swap_b32_e32 v151, v150
	v_max_f32_e32 v150, v150, v151
	v_cmp_lt_f32_e64 s[4:5], s9, v150
	s_nop 1
	v_cndmask_b32_e64 v174, 0, v150, s[4:5]
	v_sub_f32_e32 v158, v158, v174
	v_sub_f32_e32 v159, v159, v174
	v_sub_f32_e32 v160, v160, v174
	v_sub_f32_e32 v161, v161, v174
	v_sub_f32_e32 v162, v162, v174
	v_sub_f32_e32 v163, v163, v174
	v_sub_f32_e32 v164, v164, v174
	v_sub_f32_e32 v165, v165, v174
	v_sub_f32_e32 v166, v166, v174
	v_sub_f32_e32 v167, v167, v174
	v_sub_f32_e32 v168, v168, v174
	v_sub_f32_e32 v169, v169, v174
	v_sub_f32_e32 v170, v170, v174
	v_sub_f32_e32 v171, v171, v174
	v_sub_f32_e32 v172, v172, v174
	v_sub_f32_e32 v173, v173, v174
	v_sub_f32_e32 v120, v120, v174
	v_sub_f32_e32 v121, v121, v174
	v_sub_f32_e32 v122, v122, v174
	v_sub_f32_e32 v123, v123, v174
	v_sub_f32_e32 v124, v124, v174
	v_sub_f32_e32 v125, v125, v174
	v_sub_f32_e32 v126, v126, v174
	v_sub_f32_e32 v127, v127, v174
	v_sub_f32_e32 v128, v128, v174
	v_sub_f32_e32 v129, v129, v174
	v_sub_f32_e32 v130, v130, v174
	v_sub_f32_e32 v131, v131, v174
	v_sub_f32_e32 v132, v132, v174
	v_sub_f32_e32 v133, v133, v174
	v_sub_f32_e32 v134, v134, v174
	v_sub_f32_e32 v135, v135, v174
	s_cmp_eq_u32 s9, 0xff800000
	s_cbranch_scc1 .LaN_nrj01
	v_sub_f32_e32 v151, 0, v174
	v_exp_f32_e32 v174, v151
	s_nop 0
	v_mul_f32_e32 v178, v178, v174
	v_pk_mul_f32 v[16:17], v[16:17], v[174:175] op_sel_hi:[1,0]
	v_pk_mul_f32 v[18:19], v[18:19], v[174:175] op_sel_hi:[1,0]
	v_pk_mul_f32 v[20:21], v[20:21], v[174:175] op_sel_hi:[1,0]
	v_pk_mul_f32 v[22:23], v[22:23], v[174:175] op_sel_hi:[1,0]
	v_pk_mul_f32 v[24:25], v[24:25], v[174:175] op_sel_hi:[1,0]
	v_pk_mul_f32 v[26:27], v[26:27], v[174:175] op_sel_hi:[1,0]
	v_pk_mul_f32 v[28:29], v[28:29], v[174:175] op_sel_hi:[1,0]
	v_pk_mul_f32 v[30:31], v[30:31], v[174:175] op_sel_hi:[1,0]
	v_pk_mul_f32 v[0:1], v[0:1], v[174:175] op_sel_hi:[1,0]
	v_pk_mul_f32 v[2:3], v[2:3], v[174:175] op_sel_hi:[1,0]
	v_pk_mul_f32 v[4:5], v[4:5], v[174:175] op_sel_hi:[1,0]
	v_pk_mul_f32 v[6:7], v[6:7], v[174:175] op_sel_hi:[1,0]
	v_pk_mul_f32 v[8:9], v[8:9], v[174:175] op_sel_hi:[1,0]
	v_pk_mul_f32 v[10:11], v[10:11], v[174:175] op_sel_hi:[1,0]
	v_pk_mul_f32 v[12:13], v[12:13], v[174:175] op_sel_hi:[1,0]
	v_pk_mul_f32 v[14:15], v[14:15], v[174:175] op_sel_hi:[1,0]
.LaN_nrj01:
	s_branch .LaN_xj0

; __device__ __forceinline__ unsigned pk2(float lo, float hi) { unsigned r; asm("v_cvt_pk_bf16_f32 %0, %1, %2" : "=v"(r) : "v"(lo), "v"(hi)); return r; }
; __device__ __forceinline__ void phase0(const Args& a, LAS unsigned char* lds) {
;     ...
;     for (int r = gw * 32; r < MTOK; r += NGW * 32) {
; #pragma unroll 1
;         for (int k = 0; k < 32; k += 4) {
;             f32x4 v[4][4];
; #pragma unroll
;             for (int u = 0; u < 4; ++u)
; #pragma unroll
;                 for (int j = 0; j < 4; ++j) v[u][j] = *(const f32x4*)(a.in[0] + (size_t)(r + k + u) * DM + 4 * lane + 256 * j);
; #pragma unroll
;             for (int u = 0; u < 4; ++u) {
;                 float s = 0.f;
; #pragma unroll
;                 for (int j = 0; j < 4; ++j) s += (v[u][j][0] * v[u][j][0] + v[u][j][1] * v[u][j][1]) + (v[u][j][2] * v[u][j][2] + v[u][j][3] * v[u][j][3]);
;                 const float rstd = rsqrtf(wave_sum(s) * (1.0f / DM) + EPS);
;                 bf16_t* orow = (bf16_t*)(a.ws + WS_H) + (size_t)(r + k + u) * DM;
; #pragma unroll
;                 for (int j = 0; j < 4; ++j) { const f32x4 gg = *(const f32x4*)(a.in[1] + 4 * lane + 256 * j); const f32x4 y = v[u][j] * rstd * gg; u32x2 w; w.x = pk2(y[0], y[1]); w.y = pk2(y[2], y[3]); *(u32x2*)(orow + 4 * lane + 256 * j) = w; }
.LBB0_416:
	s_or_b64 exec, exec, s[14:15]
	s_movk_i32 s0, 0x800
	v_cmp_gt_i32_e32 vcc, s0, v202
	s_and_saveexec_b64 s[0:1], vcc
	v_readlane_b32 s20, v254, 21
	s_mov_b64 s[28:29], 0x4000
	s_mov_b64 s[12:13], 0x2000
	v_readlane_b32 s21, v254, 22
	s_cbranch_execz .LBB0_421
	v_and_b32_e32 v1, 64, v234
	v_add_u32_e32 v1, 64, v1
	v_xor_b32_e32 v2, 1, v234
	v_cmp_lt_i32_e32 vcc, v2, v1
	v_lshlrev_b32_e32 v68, 5, v202
	v_mov_b32_e32 v3, v155
	v_cndmask_b32_e32 v2, v234, v2, vcc
	v_lshlrev_b32_e32 v91, 2, v2
	v_xor_b32_e32 v2, 2, v234
	v_cmp_lt_i32_e32 vcc, v2, v1
	s_mov_b64 s[4:5], 0x3f8a000
	v_ashrrev_i32_e32 v69, 31, v68
	v_cndmask_b32_e32 v2, v234, v2, vcc
	v_lshlrev_b32_e32 v92, 2, v2
	v_xor_b32_e32 v2, 4, v234
	v_cmp_lt_i32_e32 vcc, v2, v1
	v_readlane_b32 s6, v254, 23
	v_lshlrev_b32_e32 v154, 4, v0
	v_cndmask_b32_e32 v2, v234, v2, vcc
	v_lshlrev_b32_e32 v93, 2, v2
	v_xor_b32_e32 v2, 8, v234
	v_cmp_lt_i32_e32 vcc, v2, v1
	v_readlane_b32 s7, v254, 24
	s_lshl_b32 s2, s87, 8
	v_cndmask_b32_e32 v2, v234, v2, vcc
	v_lshlrev_b32_e32 v94, 2, v2
	v_xor_b32_e32 v2, 16, v234
	v_cmp_lt_i32_e32 vcc, v2, v1
	v_lshl_add_u64 v[70:71], s[6:7], 0, v[154:155]
	s_ashr_i32 s3, s2, 31
	v_cndmask_b32_e32 v2, v234, v2, vcc
	v_lshlrev_b32_e32 v95, 2, v2
	v_xor_b32_e32 v2, 32, v234
	v_cmp_lt_i32_e32 vcc, v2, v1
	s_mov_b64 s[8:9], 0
	s_nop 0
	v_cndmask_b32_e32 v1, v234, v2, vcc
	v_lshlrev_b32_e32 v2, 3, v0
	v_lshl_add_u64 v[2:3], s[34:35], 0, v[2:3]
	v_lshl_add_u64 v[72:73], v[2:3], 0, s[4:5]
	v_readlane_b32 s4, v254, 25
	v_lshlrev_b64 v[2:3], 12, v[68:69]
	v_readlane_b32 s5, v254, 26
	v_lshl_or_b32 v2, v0, 4, v2
	v_lshl_add_u64 v[2:3], s[6:7], 0, v[2:3]
	v_lshl_add_u64 v[74:75], s[4:5], 0, v[154:155]
	global_load_dwordx4 v[104:107], v[74:75], off
	global_load_dwordx4 v[108:111], v[74:75], off offset:1024
	global_load_dwordx4 v[112:115], v[74:75], off offset:2048
	global_load_dwordx4 v[116:119], v[74:75], off offset:3072
	s_mov_b64 s[4:5], 0xc00
	v_lshl_add_u64 v[76:77], v[2:3], 0, s[4:5]
	v_lshlrev_b64 v[2:3], 11, v[68:69]
	v_lshl_or_b32 v2, v0, 3, v2
	v_lshlrev_b32_e32 v96, 2, v1
	v_lshl_add_u64 v[0:1], s[34:35], 0, v[2:3]
	s_mov_b64 s[6:7], 0x3f8a400
	s_lshl_b64 s[4:5], s[2:3], 12
	v_lshl_add_u64 v[78:79], v[0:1], 0, s[6:7]
	s_lshl_b64 s[6:7], s[2:3], 11

; __device__ __forceinline__ unsigned pk2(float lo, float hi) { unsigned r; asm("v_cvt_pk_bf16_f32 %0, %1, %2" : "=v"(r) : "v"(lo), "v"(hi)); return r; }
; __device__ __forceinline__ void phase0(const Args& a, LAS unsigned char* lds) {
;     ...
;         for (int k = 0; k < 32; k += 4) {
;             f32x4 v[4][4];
; #pragma unroll
;             for (int u = 0; u < 4; ++u)
; #pragma unroll
;                 for (int j = 0; j < 4; ++j) v[u][j] = *(const f32x4*)(a.in[0] + (size_t)(r + k + u) * DM + 4 * lane + 256 * j);
; #pragma unroll
;             for (int u = 0; u < 4; ++u) {
;                 float s = 0.f;
; #pragma unroll
;                 for (int j = 0; j < 4; ++j) s += (v[u][j][0] * v[u][j][0] + v[u][j][1] * v[u][j][1]) + (v[u][j][2] * v[u][j][2] + v[u][j][3] * v[u][j][3]);
;                 const float rstd = rsqrtf(wave_sum(s) * (1.0f / DM) + EPS);
;                 bf16_t* orow = (bf16_t*)(a.ws + WS_H) + (size_t)(r + k + u) * DM;
; #pragma unroll
;                 for (int j = 0; j < 4; ++j) { const f32x4 gg = *(const f32x4*)(a.in[1] + 4 * lane + 256 * j); const f32x4 y = v[u][j] * rstd * gg; u32x2 w; w.x = pk2(y[0], y[1]); w.y = pk2(y[2], y[3]); *(u32x2*)(orow + 4 * lane + 256 * j) = w; }
.LBB0_419:
	global_load_dwordx4 v[60:63], v[82:83], off offset:-3072
	global_load_dwordx4 v[56:59], v[82:83], off offset:-2048
	global_load_dwordx4 v[52:55], v[82:83], off offset:-1024
	global_load_dwordx4 v[48:51], v[82:83], off
	v_add_u32_e32 v2, s3, v68
	v_add_u32_e32 v88, 5, v2
	v_ashrrev_i32_e32 v89, 31, v88
	v_lshlrev_b64 v[0:1], 12, v[88:89]
	v_add_u32_e32 v86, 6, v2
	v_lshl_add_u64 v[0:1], v[70:71], 0, v[0:1]
	v_ashrrev_i32_e32 v87, 31, v86
	global_load_dwordx4 v[44:47], v[0:1], off
	global_load_dwordx4 v[40:43], v[0:1], off offset:1024
	global_load_dwordx4 v[36:39], v[0:1], off offset:2048
	global_load_dwordx4 v[32:35], v[0:1], off offset:3072
	v_lshlrev_b64 v[0:1], 12, v[86:87]
	v_add_u32_e32 v84, 7, v2
	v_lshl_add_u64 v[0:1], v[70:71], 0, v[0:1]
	v_ashrrev_i32_e32 v85, 31, v84
	global_load_dwordx4 v[28:31], v[0:1], off
	global_load_dwordx4 v[24:27], v[0:1], off offset:1024
	global_load_dwordx4 v[20:23], v[0:1], off offset:2048
	global_load_dwordx4 v[16:19], v[0:1], off offset:3072
	v_lshlrev_b64 v[0:1], 12, v[84:85]
	v_lshl_add_u64 v[0:1], v[70:71], 0, v[0:1]
	global_load_dwordx4 v[12:15], v[0:1], off
	global_load_dwordx4 v[8:11], v[0:1], off offset:1024
	global_load_dwordx4 v[4:7], v[0:1], off offset:2048
	s_nop 0
	global_load_dwordx4 v[0:3], v[0:1], off offset:3072
	s_add_i32 s3, s3, 4
	v_lshl_add_u64 v[82:83], v[82:83], 0, s[28:29]
	s_cmp_gt_u32 s3, 27
	s_waitcnt vmcnt(0)
	v_pk_mul_f32 v[64:65], v[62:63], v[62:63]
	v_pk_mul_f32 v[66:67], v[60:61], v[60:61]
	v_mul_f32_e32 v69, v48, v48
	v_pk_mov_b32 v[98:99], v[66:67], v[64:65] op_sel:[1,0]
	v_mov_b32_e32 v67, v65
	v_pk_add_f32 v[64:65], v[98:99], v[66:67]
	v_pk_mul_f32 v[66:67], v[58:59], v[58:59]
	v_pk_mul_f32 v[98:99], v[56:57], v[56:57]
	v_mul_f32_e32 v90, v49, v49
	v_pk_mov_b32 v[100:101], v[98:99], v[66:67] op_sel:[1,0]
	v_mov_b32_e32 v99, v67
	v_pk_add_f32 v[66:67], v[100:101], v[98:99]
	v_pk_add_f32 v[64:65], v[64:65], v[64:65] op_sel:[0,1] op_sel_hi:[1,0]
	v_pk_add_f32 v[66:67], v[66:67], v[66:67] op_sel:[0,1] op_sel_hi:[1,0]
	v_mov_b32_e32 v65, v69
	v_mov_b32_e32 v67, v90
	v_pk_add_f32 v[64:65], v[64:65], v[66:67]
	v_mul_f32_e32 v66, v53, v53
	v_mul_f32_e32 v90, v55, v55
	v_mul_f32_e32 v97, v50, v50
	v_mul_f32_e32 v100, v51, v51
	v_pk_fma_f32 v[66:67], v[52:53], v[52:53], v[66:67] op_sel_hi:[1,1,0]
	v_pk_fma_f32 v[98:99], v[54:55], v[54:55], v[90:91] op_sel_hi:[1,1,0]
	v_mov_b32_e32 v67, v97
	v_mov_b32_e32 v99, v100
	v_pk_add_f32 v[66:67], v[66:67], v[98:99]
	s_nop 0
	v_pk_add_f32 v[64:65], v[64:65], v[66:67]
	s_nop 0
	v_add_f32_e32 v64, v64, v65
	ds_bpermute_b32 v65, v91, v64
	s_waitcnt lgkmcnt(0)
	v_add_f32_e32 v64, v64, v65
	ds_bpermute_b32 v65, v92, v64
	s_waitcnt lgkmcnt(0)
	v_add_f32_e32 v64, v64, v65
	ds_bpermute_b32 v65, v93, v64
	s_waitcnt lgkmcnt(0)
	v_add_f32_e32 v64, v64, v65
	ds_bpermute_b32 v65, v94, v64
	s_waitcnt lgkmcnt(0)
	v_add_f32_e32 v64, v64, v65
	ds_bpermute_b32 v65, v95, v64
	s_waitcnt lgkmcnt(0)
	v_add_f32_e32 v64, v64, v65
	ds_bpermute_b32 v65, v96, v64
	s_waitcnt lgkmcnt(0)
	v_add_f32_e32 v64, v64, v65
	v_fmamk_f32 v64, v64, 0x3a800000, v227
	v_cmp_gt_f32_e32 vcc, s33, v64
	v_mul_f32_e32 v65, 0x4b800000, v64
	s_nop 0
	v_cndmask_b32_e32 v64, v64, v65, vcc
	v_rsq_f32_e32 v64, v64
	s_nop 0
	v_mul_f32_e32 v65, 0x45800000, v64
	v_cndmask_b32_e32 v90, v64, v65, vcc
	v_mov_b32_e32 v64, v104
	v_mov_b32_e32 v65, v105
	v_mov_b32_e32 v66, v106
	v_mov_b32_e32 v67, v107
	v_pk_mul_f32 v[60:61], v[60:61], v[90:91] op_sel_hi:[1,0]
	v_pk_mul_f32 v[62:63], v[62:63], v[90:91] op_sel_hi:[1,0]
	v_pk_mul_f32 v[56:57], v[56:57], v[90:91] op_sel_hi:[1,0]
	v_pk_mul_f32 v[58:59], v[58:59], v[90:91] op_sel_hi:[1,0]
	v_pk_mul_f32 v[52:53], v[52:53], v[90:91] op_sel_hi:[1,0]
	v_pk_mul_f32 v[54:55], v[54:55], v[90:91] op_sel_hi:[1,0]
	v_pk_mul_f32 v[48:49], v[48:49], v[90:91] op_sel_hi:[1,0]
	v_pk_mul_f32 v[50:51], v[50:51], v[90:91] op_sel_hi:[1,0]
	v_pk_mul_f32 v[60:61], v[64:65], v[60:61]
	v_pk_mul_f32 v[62:63], v[66:67], v[62:63]
	v_cvt_pk_bf16_f32 v60, v60, v61
	s_nop 0
	v_cvt_pk_bf16_f32 v61, v62, v63
	global_store_dwordx2 v[80:81], v[60:61], off offset:-1024
	v_mov_b32_e32 v60, v108
	v_mov_b32_e32 v61, v109
	v_mov_b32_e32 v62, v110
	v_mov_b32_e32 v63, v111
	v_pk_mul_f32 v[56:57], v[60:61], v[56:57]
	v_pk_mul_f32 v[58:59], v[62:63], v[58:59]
	v_cvt_pk_bf16_f32 v56, v56, v57
	s_nop 0
	v_cvt_pk_bf16_f32 v57, v58, v59
	global_store_dwordx2 v[80:81], v[56:57], off offset:-512
	v_mov_b32_e32 v56, v112
	v_mov_b32_e32 v57, v113
	v_mov_b32_e32 v58, v114
	v_mov_b32_e32 v59, v115
	v_pk_mul_f32 v[52:53], v[56:57], v[52:53]
	v_pk_mul_f32 v[54:55], v[58:59], v[54:55]
	v_cvt_pk_bf16_f32 v52, v52, v53
	s_nop 0
	v_cvt_pk_bf16_f32 v53, v54, v55
	global_store_dwordx2 v[80:81], v[52:53], off
	v_mov_b32_e32 v52, v116
	v_mov_b32_e32 v53, v117
	v_mov_b32_e32 v54, v118
	v_mov_b32_e32 v55, v119
	v_pk_mul_f32 v[48:49], v[48:49], v[52:53]
	v_pk_mul_f32 v[50:51], v[50:51], v[54:55]
	v_cvt_pk_bf16_f32 v48, v48, v49
	s_nop 0
	v_cvt_pk_bf16_f32 v49, v50, v51
	global_store_dwordx2 v[80:81], v[48:49], off offset:512
	v_pk_mul_f32 v[48:49], v[46:47], v[46:47]
	v_pk_mul_f32 v[50:51], v[44:45], v[44:45]
	v_lshl_add_u64 v[80:81], v[80:81], 0, s[12:13]
	v_pk_mov_b32 v[52:53], v[50:51], v[48:49] op_sel:[1,0]
	v_mov_b32_e32 v51, v49
	v_pk_add_f32 v[48:49], v[52:53], v[50:51]
	v_pk_mul_f32 v[50:51], v[42:43], v[42:43]
	v_pk_mul_f32 v[52:53], v[40:41], v[40:41]
	v_pk_add_f32 v[48:49], v[48:49], v[48:49] op_sel:[0,1] op_sel_hi:[1,0]
	v_pk_mov_b32 v[54:55], v[52:53], v[50:51] op_sel:[1,0]
	v_mov_b32_e32 v53, v51
	v_pk_add_f32 v[50:51], v[54:55], v[52:53]
	v_mul_f32_e32 v52, v32, v32
	v_mul_f32_e32 v53, v33, v33
	v_pk_add_f32 v[50:51], v[50:51], v[50:51] op_sel:[0,1] op_sel_hi:[1,0]
	v_mov_b32_e32 v49, v52
	v_mov_b32_e32 v51, v53
	v_pk_add_f32 v[48:49], v[48:49], v[50:51]
	v_mul_f32_e32 v50, v37, v37
	v_mul_f32_e32 v52, v39, v39
	v_mul_f32_e32 v54, v34, v34
	v_mul_f32_e32 v55, v35, v35
	v_pk_fma_f32 v[50:51], v[36:37], v[36:37], v[50:51] op_sel_hi:[1,1,0]
	v_pk_fma_f32 v[52:53], v[38:39], v[38:39], v[52:53] op_sel_hi:[1,1,0]
	v_mov_b32_e32 v51, v54
	v_mov_b32_e32 v53, v55
	v_pk_add_f32 v[50:51], v[50:51], v[52:53]
	v_mov_b32_e32 v52, v104
	v_mov_b32_e32 v53, v105
	v_mov_b32_e32 v54, v106
	v_mov_b32_e32 v55, v107
	v_pk_add_f32 v[48:49], v[48:49], v[50:51]
	v_lshlrev_b64 v[50:51], 11, v[88:89]
	v_add_f32_e32 v48, v48, v49
	ds_bpermute_b32 v49, v91, v48
	v_lshl_add_u64 v[50:51], v[72:73], 0, v[50:51]
	s_waitcnt lgkmcnt(0)
; __device__ __forceinline__ unsigned pk2(float lo, float hi) { unsigned r; asm("v_cvt_pk_bf16_f32 %0, %1, %2" : "=v"(r) : "v"(lo), "v"(hi)); return r; }
; __device__ __forceinline__ void phase0(const Args& a, LAS unsigned char* lds) {
;     ...
;             for (int u = 0; u < 4; ++u) {
;                 float s = 0.f;
; #pragma unroll
;                 for (int j = 0; j < 4; ++j) s += (v[u][j][0] * v[u][j][0] + v[u][j][1] * v[u][j][1]) + (v[u][j][2] * v[u][j][2] + v[u][j][3] * v[u][j][3]);
;                 const float rstd = rsqrtf(wave_sum(s) * (1.0f / DM) + EPS);
;                 bf16_t* orow = (bf16_t*)(a.ws + WS_H) + (size_t)(r + k + u) * DM;
; #pragma unroll
;                 for (int j = 0; j < 4; ++j) { const f32x4 gg = *(const f32x4*)(a.in[1] + 4 * lane + 256 * j); const f32x4 y = v[u][j] * rstd * gg; u32x2 w; w.x = pk2(y[0], y[1]); w.y = pk2(y[2], y[3]); *(u32x2*)(orow + 4 * lane + 256 * j) = w; }
	v_add_f32_e32 v48, v48, v49
	ds_bpermute_b32 v49, v92, v48
	s_waitcnt lgkmcnt(0)
	v_add_f32_e32 v48, v48, v49
	ds_bpermute_b32 v49, v93, v48
	s_waitcnt lgkmcnt(0)
	v_add_f32_e32 v48, v48, v49
	ds_bpermute_b32 v49, v94, v48
	s_waitcnt lgkmcnt(0)
	v_add_f32_e32 v48, v48, v49
	ds_bpermute_b32 v49, v95, v48
	s_waitcnt lgkmcnt(0)
	v_add_f32_e32 v48, v48, v49
	ds_bpermute_b32 v49, v96, v48
	s_waitcnt lgkmcnt(0)
	v_add_f32_e32 v48, v48, v49
	v_fmamk_f32 v48, v48, 0x3a800000, v227
	v_cmp_gt_f32_e32 vcc, s33, v48
	v_mul_f32_e32 v49, 0x4b800000, v48
	s_nop 0
	v_cndmask_b32_e32 v48, v48, v49, vcc
	v_rsq_f32_e32 v48, v48
	s_nop 0
	v_mul_f32_e32 v49, 0x45800000, v48
	v_cndmask_b32_e32 v48, v48, v49, vcc
	v_pk_mul_f32 v[44:45], v[44:45], v[48:49] op_sel_hi:[1,0]
	v_pk_mul_f32 v[46:47], v[46:47], v[48:49] op_sel_hi:[1,0]
	v_pk_mul_f32 v[40:41], v[40:41], v[48:49] op_sel_hi:[1,0]
	v_pk_mul_f32 v[42:43], v[42:43], v[48:49] op_sel_hi:[1,0]
	v_pk_mul_f32 v[36:37], v[36:37], v[48:49] op_sel_hi:[1,0]
	v_pk_mul_f32 v[38:39], v[38:39], v[48:49] op_sel_hi:[1,0]
	v_pk_mul_f32 v[32:33], v[32:33], v[48:49] op_sel_hi:[1,0]
	v_pk_mul_f32 v[34:35], v[34:35], v[48:49] op_sel_hi:[1,0]
	v_pk_mul_f32 v[44:45], v[52:53], v[44:45]
	v_pk_mul_f32 v[46:47], v[54:55], v[46:47]
	v_cvt_pk_bf16_f32 v44, v44, v45
	s_nop 0
	v_cvt_pk_bf16_f32 v45, v46, v47
	global_store_dwordx2 v[50:51], v[44:45], off
	v_mov_b32_e32 v44, v108
	v_mov_b32_e32 v45, v109
	v_mov_b32_e32 v46, v110
	v_mov_b32_e32 v47, v111
	v_pk_mul_f32 v[40:41], v[44:45], v[40:41]
	v_pk_mul_f32 v[42:43], v[46:47], v[42:43]
	v_cvt_pk_bf16_f32 v40, v40, v41
	s_nop 0
	v_cvt_pk_bf16_f32 v41, v42, v43
	global_store_dwordx2 v[50:51], v[40:41], off offset:512
	v_mov_b32_e32 v40, v112
	v_mov_b32_e32 v41, v113
	v_mov_b32_e32 v42, v114
	v_mov_b32_e32 v43, v115
	v_pk_mul_f32 v[36:37], v[40:41], v[36:37]
	v_pk_mul_f32 v[38:39], v[42:43], v[38:39]
	v_cvt_pk_bf16_f32 v36, v36, v37
	s_nop 0
	v_cvt_pk_bf16_f32 v37, v38, v39
	global_store_dwordx2 v[50:51], v[36:37], off offset:1024
	v_mov_b32_e32 v36, v116
	v_mov_b32_e32 v37, v117
	v_mov_b32_e32 v38, v118
	v_mov_b32_e32 v39, v119
	v_pk_mul_f32 v[32:33], v[32:33], v[36:37]
	v_pk_mul_f32 v[34:35], v[34:35], v[38:39]
	v_cvt_pk_bf16_f32 v32, v32, v33
	s_nop 0
	v_cvt_pk_bf16_f32 v33, v34, v35
	global_store_dwordx2 v[50:51], v[32:33], off offset:1536
	v_pk_mul_f32 v[32:33], v[30:31], v[30:31]
	v_pk_mul_f32 v[34:35], v[28:29], v[28:29]
	s_nop 0
	v_pk_mov_b32 v[36:37], v[34:35], v[32:33] op_sel:[1,0]
	v_mov_b32_e32 v35, v33
	v_pk_add_f32 v[32:33], v[36:37], v[34:35]
	v_pk_mul_f32 v[34:35], v[26:27], v[26:27]
	v_pk_mul_f32 v[36:37], v[24:25], v[24:25]
	v_pk_add_f32 v[32:33], v[32:33], v[32:33] op_sel:[0,1] op_sel_hi:[1,0]
	v_pk_mov_b32 v[38:39], v[36:37], v[34:35] op_sel:[1,0]
	v_mov_b32_e32 v37, v35
	v_pk_add_f32 v[34:35], v[38:39], v[36:37]
	v_mul_f32_e32 v36, v16, v16
	v_mul_f32_e32 v37, v17, v17
	v_pk_add_f32 v[34:35], v[34:35], v[34:35] op_sel:[0,1] op_sel_hi:[1,0]
	v_mov_b32_e32 v33, v36
	v_mov_b32_e32 v35, v37
	v_pk_add_f32 v[32:33], v[32:33], v[34:35]
	v_mul_f32_e32 v34, v21, v21
	v_mul_f32_e32 v36, v23, v23
	v_mul_f32_e32 v38, v18, v18
	v_mul_f32_e32 v39, v19, v19
	v_pk_fma_f32 v[34:35], v[20:21], v[20:21], v[34:35] op_sel_hi:[1,1,0]
	v_pk_fma_f32 v[36:37], v[22:23], v[22:23], v[36:37] op_sel_hi:[1,1,0]
	v_mov_b32_e32 v35, v38
	v_mov_b32_e32 v37, v39
	v_pk_add_f32 v[34:35], v[34:35], v[36:37]
	v_mov_b32_e32 v36, v104
	v_mov_b32_e32 v37, v105
	v_mov_b32_e32 v38, v106
	v_mov_b32_e32 v39, v107
	v_pk_add_f32 v[32:33], v[32:33], v[34:35]
	v_lshlrev_b64 v[34:35], 11, v[86:87]
	v_add_f32_e32 v32, v32, v33
	ds_bpermute_b32 v33, v91, v32
	v_lshl_add_u64 v[34:35], v[72:73], 0, v[34:35]
	s_waitcnt lgkmcnt(0)
	v_add_f32_e32 v32, v32, v33
	ds_bpermute_b32 v33, v92, v32
	s_waitcnt lgkmcnt(0)
	v_add_f32_e32 v32, v32, v33
	ds_bpermute_b32 v33, v93, v32
	s_waitcnt lgkmcnt(0)
	v_add_f32_e32 v32, v32, v33
	ds_bpermute_b32 v33, v94, v32
	s_waitcnt lgkmcnt(0)
	v_add_f32_e32 v32, v32, v33
	ds_bpermute_b32 v33, v95, v32
	s_waitcnt lgkmcnt(0)
	v_add_f32_e32 v32, v32, v33
	ds_bpermute_b32 v33, v96, v32
	s_waitcnt lgkmcnt(0)
; __device__ __forceinline__ unsigned pk2(float lo, float hi) { unsigned r; asm("v_cvt_pk_bf16_f32 %0, %1, %2" : "=v"(r) : "v"(lo), "v"(hi)); return r; }
; __device__ __forceinline__ void phase0(const Args& a, LAS unsigned char* lds) {
;     ...
;         for (int k = 0; k < 32; k += 4) {
;             f32x4 v[4][4];
; #pragma unroll
;             for (int u = 0; u < 4; ++u)
; #pragma unroll
;                 for (int j = 0; j < 4; ++j) v[u][j] = *(const f32x4*)(a.in[0] + (size_t)(r + k + u) * DM + 4 * lane + 256 * j);
; #pragma unroll
;             for (int u = 0; u < 4; ++u) {
;                 float s = 0.f;
; #pragma unroll
;                 for (int j = 0; j < 4; ++j) s += (v[u][j][0] * v[u][j][0] + v[u][j][1] * v[u][j][1]) + (v[u][j][2] * v[u][j][2] + v[u][j][3] * v[u][j][3]);
;                 const float rstd = rsqrtf(wave_sum(s) * (1.0f / DM) + EPS);
;                 bf16_t* orow = (bf16_t*)(a.ws + WS_H) + (size_t)(r + k + u) * DM;
; #pragma unroll
;                 for (int j = 0; j < 4; ++j) { const f32x4 gg = *(const f32x4*)(a.in[1] + 4 * lane + 256 * j); const f32x4 y = v[u][j] * rstd * gg; u32x2 w; w.x = pk2(y[0], y[1]); w.y = pk2(y[2], y[3]); *(u32x2*)(orow + 4 * lane + 256 * j) = w; }
	v_add_f32_e32 v32, v32, v33
	v_fmamk_f32 v32, v32, 0x3a800000, v227
	v_cmp_gt_f32_e32 vcc, s33, v32
	v_mul_f32_e32 v33, 0x4b800000, v32
	s_nop 0
	v_cndmask_b32_e32 v32, v32, v33, vcc
	v_rsq_f32_e32 v32, v32
	s_nop 0
	v_mul_f32_e32 v33, 0x45800000, v32
	v_cndmask_b32_e32 v32, v32, v33, vcc
	v_pk_mul_f32 v[28:29], v[28:29], v[32:33] op_sel_hi:[1,0]
	v_pk_mul_f32 v[30:31], v[30:31], v[32:33] op_sel_hi:[1,0]
	v_pk_mul_f32 v[24:25], v[24:25], v[32:33] op_sel_hi:[1,0]
	v_pk_mul_f32 v[26:27], v[26:27], v[32:33] op_sel_hi:[1,0]
	v_pk_mul_f32 v[20:21], v[20:21], v[32:33] op_sel_hi:[1,0]
	v_pk_mul_f32 v[22:23], v[22:23], v[32:33] op_sel_hi:[1,0]
	v_pk_mul_f32 v[16:17], v[16:17], v[32:33] op_sel_hi:[1,0]
	v_pk_mul_f32 v[18:19], v[18:19], v[32:33] op_sel_hi:[1,0]
	v_pk_mul_f32 v[28:29], v[36:37], v[28:29]
	v_pk_mul_f32 v[30:31], v[38:39], v[30:31]
	v_cvt_pk_bf16_f32 v28, v28, v29
	s_nop 0
	v_cvt_pk_bf16_f32 v29, v30, v31
	global_store_dwordx2 v[34:35], v[28:29], off
	v_mov_b32_e32 v28, v108
	v_mov_b32_e32 v29, v109
	v_mov_b32_e32 v30, v110
	v_mov_b32_e32 v31, v111
	v_pk_mul_f32 v[24:25], v[28:29], v[24:25]
	v_pk_mul_f32 v[26:27], v[30:31], v[26:27]
	v_cvt_pk_bf16_f32 v24, v24, v25
	s_nop 0
	v_cvt_pk_bf16_f32 v25, v26, v27
	global_store_dwordx2 v[34:35], v[24:25], off offset:512
	v_mov_b32_e32 v24, v112
	v_mov_b32_e32 v25, v113
	v_mov_b32_e32 v26, v114
	v_mov_b32_e32 v27, v115
	v_pk_mul_f32 v[20:21], v[24:25], v[20:21]
	v_pk_mul_f32 v[22:23], v[26:27], v[22:23]
	v_cvt_pk_bf16_f32 v20, v20, v21
	s_nop 0
	v_cvt_pk_bf16_f32 v21, v22, v23
	global_store_dwordx2 v[34:35], v[20:21], off offset:1024
	v_mov_b32_e32 v20, v116
	v_mov_b32_e32 v21, v117
	v_mov_b32_e32 v22, v118
	v_mov_b32_e32 v23, v119
	v_pk_mul_f32 v[16:17], v[16:17], v[20:21]
	v_pk_mul_f32 v[18:19], v[18:19], v[22:23]
	v_cvt_pk_bf16_f32 v16, v16, v17
	s_nop 0
	v_cvt_pk_bf16_f32 v17, v18, v19
	global_store_dwordx2 v[34:35], v[16:17], off offset:1536
	v_pk_mul_f32 v[16:17], v[14:15], v[14:15]
	v_pk_mul_f32 v[18:19], v[12:13], v[12:13]
	s_nop 0
	v_pk_mov_b32 v[20:21], v[18:19], v[16:17] op_sel:[1,0]
	v_mov_b32_e32 v19, v17
	v_pk_add_f32 v[16:17], v[20:21], v[18:19]
	v_pk_mul_f32 v[18:19], v[10:11], v[10:11]
	v_pk_mul_f32 v[20:21], v[8:9], v[8:9]
	v_pk_add_f32 v[16:17], v[16:17], v[16:17] op_sel:[0,1] op_sel_hi:[1,0]
	v_pk_mov_b32 v[22:23], v[20:21], v[18:19] op_sel:[1,0]
	v_mov_b32_e32 v21, v19
	v_pk_add_f32 v[18:19], v[22:23], v[20:21]
	v_mul_f32_e32 v20, v0, v0
	v_mul_f32_e32 v21, v1, v1
	v_pk_add_f32 v[18:19], v[18:19], v[18:19] op_sel:[0,1] op_sel_hi:[1,0]
	v_mov_b32_e32 v17, v20
	v_mov_b32_e32 v19, v21
	v_pk_add_f32 v[16:17], v[16:17], v[18:19]
	v_mul_f32_e32 v18, v5, v5
	v_mul_f32_e32 v20, v7, v7
	v_mul_f32_e32 v22, v2, v2
	v_mul_f32_e32 v23, v3, v3
	v_pk_fma_f32 v[18:19], v[4:5], v[4:5], v[18:19] op_sel_hi:[1,1,0]
	v_pk_fma_f32 v[20:21], v[6:7], v[6:7], v[20:21] op_sel_hi:[1,1,0]
	v_mov_b32_e32 v19, v22
	v_mov_b32_e32 v21, v23
	v_pk_add_f32 v[18:19], v[18:19], v[20:21]
	v_mov_b32_e32 v20, v104
	v_mov_b32_e32 v21, v105
	v_mov_b32_e32 v22, v106
	v_mov_b32_e32 v23, v107
	v_pk_add_f32 v[16:17], v[16:17], v[18:19]
	v_lshlrev_b64 v[18:19], 11, v[84:85]
	v_add_f32_e32 v16, v16, v17
	ds_bpermute_b32 v17, v91, v16
	v_lshl_add_u64 v[18:19], v[72:73], 0, v[18:19]
	s_waitcnt lgkmcnt(0)
	v_add_f32_e32 v16, v16, v17
	ds_bpermute_b32 v17, v92, v16
	s_waitcnt lgkmcnt(0)
	v_add_f32_e32 v16, v16, v17
	ds_bpermute_b32 v17, v93, v16
	s_waitcnt lgkmcnt(0)
	v_add_f32_e32 v16, v16, v17
	ds_bpermute_b32 v17, v94, v16
	s_waitcnt lgkmcnt(0)
	v_add_f32_e32 v16, v16, v17
	ds_bpermute_b32 v17, v95, v16
	s_waitcnt lgkmcnt(0)
	v_add_f32_e32 v16, v16, v17
	ds_bpermute_b32 v17, v96, v16
	s_waitcnt lgkmcnt(0)
	v_add_f32_e32 v16, v16, v17
	v_fmamk_f32 v16, v16, 0x3a800000, v227
	v_cmp_gt_f32_e32 vcc, s33, v16
	v_mul_f32_e32 v17, 0x4b800000, v16
	s_nop 0
	v_cndmask_b32_e32 v16, v16, v17, vcc
	v_rsq_f32_e32 v16, v16
	s_nop 0
	v_mul_f32_e32 v17, 0x45800000, v16
	v_cndmask_b32_e32 v16, v16, v17, vcc
	v_pk_mul_f32 v[12:13], v[12:13], v[16:17] op_sel_hi:[1,0]
	v_pk_mul_f32 v[14:15], v[14:15], v[16:17] op_sel_hi:[1,0]
	v_pk_mul_f32 v[8:9], v[8:9], v[16:17] op_sel_hi:[1,0]
	v_pk_mul_f32 v[10:11], v[10:11], v[16:17] op_sel_hi:[1,0]
	v_pk_mul_f32 v[4:5], v[4:5], v[16:17] op_sel_hi:[1,0]
	v_pk_mul_f32 v[6:7], v[6:7], v[16:17] op_sel_hi:[1,0]
	v_pk_mul_f32 v[0:1], v[0:1], v[16:17] op_sel_hi:[1,0]
	v_pk_mul_f32 v[2:3], v[2:3], v[16:17] op_sel_hi:[1,0]
	v_pk_mul_f32 v[12:13], v[20:21], v[12:13]
	v_pk_mul_f32 v[14:15], v[22:23], v[14:15]
	v_cvt_pk_bf16_f32 v12, v12, v13
	s_nop 0
	v_cvt_pk_bf16_f32 v13, v14, v15
	global_store_dwordx2 v[18:19], v[12:13], off
	v_mov_b32_e32 v12, v108
	v_mov_b32_e32 v13, v109
	v_mov_b32_e32 v14, v110
	v_mov_b32_e32 v15, v111
	v_pk_mul_f32 v[8:9], v[12:13], v[8:9]
	v_pk_mul_f32 v[10:11], v[14:15], v[10:11]
	v_cvt_pk_bf16_f32 v8, v8, v9
	s_nop 0
	v_cvt_pk_bf16_f32 v9, v10, v11
	global_store_dwordx2 v[18:19], v[8:9], off offset:512
	v_mov_b32_e32 v8, v112
	v_mov_b32_e32 v9, v113
	v_mov_b32_e32 v10, v114
	v_mov_b32_e32 v11, v115
	v_pk_mul_f32 v[4:5], v[8:9], v[4:5]
	v_pk_mul_f32 v[6:7], v[10:11], v[6:7]
	v_cvt_pk_bf16_f32 v4, v4, v5
	s_nop 0
	v_cvt_pk_bf16_f32 v5, v6, v7
	global_store_dwordx2 v[18:19], v[4:5], off offset:1024
	v_mov_b32_e32 v4, v116
	v_mov_b32_e32 v5, v117
	v_mov_b32_e32 v6, v118
	v_mov_b32_e32 v7, v119
	v_pk_mul_f32 v[0:1], v[0:1], v[4:5]
	v_pk_mul_f32 v[2:3], v[2:3], v[6:7]
	v_cvt_pk_bf16_f32 v0, v0, v1
	s_nop 0
	v_cvt_pk_bf16_f32 v1, v2, v3
	global_store_dwordx2 v[18:19], v[0:1], off offset:1536
	s_cbranch_scc0 .LBB0_419
	v_add_u32_e32 v68, s2, v68
	v_cmp_lt_i32_e32 vcc, s71, v68
	v_lshl_add_u64 v[76:77], v[76:77], 0, s[4:5]
	s_or_b64 s[8:9], vcc, s[8:9]
	v_lshl_add_u64 v[78:79], v[78:79], 0, s[6:7]
	s_andn2_b64 exec, exec, s[8:9]
	s_cbranch_execnz .LBB0_418
